# S3/S6/S13 (write-after-read-only seams) made XCD-local; the cross-XCD arrival check is deferred to just before each tile's first stores (LGEN snapshot by LDS-DMA in the last K iteration, synchronous p
# baseline (speedup 1.0000x reference)
; #define PG8_WAIT_V8_STRICT() asm volatile("s_waitcnt vmcnt(8)" ::: "memory")
; template <class Epi, class Sched, bool ALIGN_EPI = false, bool SP2 = false>
; __device__ __forceinline__ void gemm_phase(PG8_LAS unsigned char* lds, const Gemm g, const Sched& S, const Epi& E, int wave_s) {
;     ...
;         for (int t = peeled ? 2 : 0; t < nt; t += 2) {
;             const bool last = (t == nt - 2);
;             const char* a1 = cA + (size_t)(t + 1) * kstep;
;             const char* a2 = last ? nA : cA + (size_t)(t + 2) * kstep; const char* b2 = last ? nB : cB + (size_t)(t + 2) * kstep;
;             const char* a3 = a2 + kstep; const char* b3 = b2 + kstep;
;             if (last && has_next) S.a_ready(nxt);
;             if constexpr (SP2) {
;             PG8_SP2_PAIR(PG8_WAIT_V8_STRICT);
.Lwsb_0:
	v_add_u32_e32 v151, s78, v146
	v_add_u32_e32 v150, s79, v146
	ds_read_b128 v[152:155], v151
	ds_read_b128 v[156:159], v151 offset:1024
	ds_read_b128 v[160:163], v151 offset:2048
	ds_read_b128 v[164:167], v151 offset:3072
	ds_read_b128 v[168:171], v150
	ds_read_b128 v[176:179], v150 offset:1024
	ds_read_b128 v[180:183], v150 offset:2048
	ds_read_b128 v[184:187], v150 offset:3072
	s_add_u32 s8, s52, 0x100
	s_addc_u32 s9, s53, 0
	s_cmp_eq_u32 s96, 12
	s_cselect_b32 s42, s93, s8
	s_cselect_b32 s43, s82, s9
	s_cselect_b32 s40, s95, s97
	s_cselect_b32 s41, s94, vcc_lo
	s_add_u32 s38, s42, 0x80
	s_addc_u32 s39, s43, 0
	s_add_u32 s52, s52, 0x40080
	s_addc_u32 s53, s53, 0
	s_add_i32 s91, s35, 0xc000
	ds_read_b128 v[188:191], v149
	ds_read_b128 v[192:195], v149 offset:1024
	ds_read_b128 v[196:199], v149 offset:2048
	ds_read_b128 v[200:203], v149 offset:3072
	ds_read_b128 v[204:207], v149 offset:4096
	ds_read_b128 v[208:211], v149 offset:5120
	ds_read_b128 v[212:215], v149 offset:6144
	ds_read_b128 v[216:219], v149 offset:7168
	s_mov_b32 m0, s91
	s_add_i32 s10, s35, 0xe000
	global_load_lds_dwordx4 v132, s[52:53]
	s_mov_b32 m0, s10
	s_nop 0
	global_load_lds_dwordx4 v136, s[52:53]
	s_waitcnt vmcnt(8)
	s_waitcnt lgkmcnt(0)
	s_barrier
	s_waitcnt lgkmcnt(0)
	v_mfma_f32_16x16x32_bf16 v[128:131], v[152:155], v[188:191], v[128:131]
	v_mfma_f32_16x16x32_bf16 v[124:127], v[160:163], v[188:191], v[124:127]
	v_mfma_f32_16x16x32_bf16 v[112:115], v[152:155], v[196:199], v[112:115]
	v_mfma_f32_16x16x32_bf16 v[108:111], v[160:163], v[196:199], v[108:111]
	v_mfma_f32_16x16x32_bf16 v[96:99], v[152:155], v[204:207], v[96:99]
	v_mfma_f32_16x16x32_bf16 v[92:95], v[160:163], v[204:207], v[92:95]
	v_mfma_f32_16x16x32_bf16 v[80:83], v[152:155], v[212:215], v[80:83]
	v_mfma_f32_16x16x32_bf16 v[76:79], v[160:163], v[212:215], v[76:79]
	v_mfma_f32_16x16x32_bf16 v[128:131], v[156:159], v[192:195], v[128:131]
	v_mfma_f32_16x16x32_bf16 v[124:127], v[164:167], v[192:195], v[124:127]
	v_mfma_f32_16x16x32_bf16 v[112:115], v[156:159], v[200:203], v[112:115]
	v_mfma_f32_16x16x32_bf16 v[108:111], v[164:167], v[200:203], v[108:111]
	v_mfma_f32_16x16x32_bf16 v[96:99], v[156:159], v[208:211], v[96:99]
	v_mfma_f32_16x16x32_bf16 v[92:95], v[164:167], v[208:211], v[92:95]
	v_mfma_f32_16x16x32_bf16 v[80:83], v[156:159], v[216:219], v[80:83]
	v_mfma_f32_16x16x32_bf16 v[76:79], v[164:167], v[216:219], v[76:79]
	v_mfma_f32_16x16x32_bf16 v[120:123], v[168:171], v[188:191], v[120:123]
	v_mfma_f32_16x16x32_bf16 v[116:119], v[180:183], v[188:191], v[116:119]
	v_mfma_f32_16x16x32_bf16 v[104:107], v[168:171], v[196:199], v[104:107]
	v_mfma_f32_16x16x32_bf16 v[100:103], v[180:183], v[196:199], v[100:103]
	v_mfma_f32_16x16x32_bf16 v[88:91], v[168:171], v[204:207], v[88:91]
	v_mfma_f32_16x16x32_bf16 v[84:87], v[180:183], v[204:207], v[84:87]
	v_mfma_f32_16x16x32_bf16 v[72:75], v[168:171], v[212:215], v[72:75]
	v_mfma_f32_16x16x32_bf16 v[68:71], v[180:183], v[212:215], v[68:71]
	v_mfma_f32_16x16x32_bf16 v[120:123], v[176:179], v[192:195], v[120:123]
	v_mfma_f32_16x16x32_bf16 v[116:119], v[184:187], v[192:195], v[116:119]
	v_mfma_f32_16x16x32_bf16 v[104:107], v[176:179], v[200:203], v[104:107]
	v_mfma_f32_16x16x32_bf16 v[100:103], v[184:187], v[200:203], v[100:103]
	v_mfma_f32_16x16x32_bf16 v[88:91], v[176:179], v[208:211], v[88:91]
	v_mfma_f32_16x16x32_bf16 v[84:87], v[184:187], v[208:211], v[84:87]
	v_mfma_f32_16x16x32_bf16 v[72:75], v[176:179], v[216:219], v[72:75]
	v_mfma_f32_16x16x32_bf16 v[68:71], v[184:187], v[216:219], v[68:71]
	s_barrier
	s_setprio 1
	s_mov_b64 s[52:53], s[40:41]
	s_add_i32 s90, s78, s58
	ds_read_b128 v[188:191], v149 offset:16384
	ds_read_b128 v[192:195], v149 offset:17408
	ds_read_b128 v[196:199], v149 offset:18432
	ds_read_b128 v[200:203], v149 offset:19456
	ds_read_b128 v[204:207], v149 offset:20480
	ds_read_b128 v[208:211], v149 offset:21504
	ds_read_b128 v[212:215], v149 offset:22528
	ds_read_b128 v[216:219], v149 offset:23552
	s_mov_b32 m0, s90
	s_add_i32 s25, s90, 0x2000
	global_load_lds_dwordx4 v134, s[52:53]
	s_mov_b64 s[98:99], s[52:53]
	s_add_u32 s52, s40, 0x40000
	s_mov_b32 m0, s25
	s_addc_u32 s53, s41, 0
	s_add_i32 s27, s79, s58
	global_load_lds_dwordx4 v138, s[98:99]
	s_mov_b32 m0, s27
	s_add_i32 s88, s27, 0x2000
	global_load_lds_dwordx4 v134, s[52:53]
	s_mov_b64 s[98:99], s[52:53]
	s_mov_b32 m0, s88
	s_mov_b64 s[52:53], s[42:43]
	global_load_lds_dwordx4 v138, s[98:99]
	s_mov_b32 m0, s35
	s_nop 0
	global_load_lds_dwordx4 v132, s[52:53]
	s_mov_b32 m0, s37
	s_nop 0
	global_load_lds_dwordx4 v136, s[52:53]
	s_setprio 0
	s_waitcnt vmcnt(8)
	s_waitcnt lgkmcnt(0)
	s_barrier
	s_waitcnt lgkmcnt(0)
	v_mfma_f32_16x16x32_bf16 v[64:67], v[152:155], v[188:191], v[64:67]
	v_mfma_f32_16x16x32_bf16 v[60:63], v[160:163], v[188:191], v[60:63]
	v_mfma_f32_16x16x32_bf16 v[48:51], v[152:155], v[196:199], v[48:51]
	v_mfma_f32_16x16x32_bf16 v[44:47], v[160:163], v[196:199], v[44:47]
	v_mfma_f32_16x16x32_bf16 v[32:35], v[152:155], v[204:207], v[32:35]
	v_mfma_f32_16x16x32_bf16 v[28:31], v[160:163], v[204:207], v[28:31]
	v_mfma_f32_16x16x32_bf16 v[16:19], v[152:155], v[212:215], v[16:19]
	v_mfma_f32_16x16x32_bf16 v[12:15], v[160:163], v[212:215], v[12:15]
	v_mfma_f32_16x16x32_bf16 v[64:67], v[156:159], v[192:195], v[64:67]
	v_mfma_f32_16x16x32_bf16 v[60:63], v[164:167], v[192:195], v[60:63]
	v_mfma_f32_16x16x32_bf16 v[48:51], v[156:159], v[200:203], v[48:51]
	v_mfma_f32_16x16x32_bf16 v[44:47], v[164:167], v[200:203], v[44:47]
	v_mfma_f32_16x16x32_bf16 v[32:35], v[156:159], v[208:211], v[32:35]
	v_mfma_f32_16x16x32_bf16 v[28:31], v[164:167], v[208:211], v[28:31]
	v_mfma_f32_16x16x32_bf16 v[16:19], v[156:159], v[216:219], v[16:19]
	v_mfma_f32_16x16x32_bf16 v[12:15], v[164:167], v[216:219], v[12:15]
	v_mfma_f32_16x16x32_bf16 v[56:59], v[168:171], v[188:191], v[56:59]
	v_mfma_f32_16x16x32_bf16 v[52:55], v[180:183], v[188:191], v[52:55]
	v_mfma_f32_16x16x32_bf16 v[40:43], v[168:171], v[196:199], v[40:43]
	v_mfma_f32_16x16x32_bf16 v[36:39], v[180:183], v[196:199], v[36:39]
	v_mfma_f32_16x16x32_bf16 v[24:27], v[168:171], v[204:207], v[24:27]
	v_mfma_f32_16x16x32_bf16 v[20:23], v[180:183], v[204:207], v[20:23]
	v_mfma_f32_16x16x32_bf16 v[8:11], v[168:171], v[212:215], v[8:11]
	v_mfma_f32_16x16x32_bf16 v[2:5], v[180:183], v[212:215], v[4:7]
	v_mfma_f32_16x16x32_bf16 v[56:59], v[176:179], v[192:195], v[56:59]
	v_mfma_f32_16x16x32_bf16 v[52:55], v[184:187], v[192:195], v[52:55]
	v_mfma_f32_16x16x32_bf16 v[40:43], v[176:179], v[200:203], v[40:43]
	v_mfma_f32_16x16x32_bf16 v[36:39], v[184:187], v[200:203], v[36:39]
	v_mfma_f32_16x16x32_bf16 v[24:27], v[176:179], v[208:211], v[24:27]
	v_mfma_f32_16x16x32_bf16 v[20:23], v[184:187], v[208:211], v[20:23]
	v_mfma_f32_16x16x32_bf16 v[8:11], v[176:179], v[216:219], v[8:11]
	v_mfma_f32_16x16x32_bf16 v[2:5], v[184:187], v[216:219], v[2:5]
	s_barrier
	s_add_i32 s92, 0, 0x18000
	s_add_i32 s52, 0, 0x1c000
	v_add_u32_e32 v152, s92, v146
	v_add_u32_e32 v153, s52, v146
	ds_read_b128 v[154:157], v152
	ds_read_b128 v[158:161], v152 offset:1024
	ds_read_b128 v[162:165], v152 offset:2048
	ds_read_b128 v[166:169], v152 offset:3072
	ds_read_b128 v[170:173], v153
	ds_read_b128 v[176:179], v153 offset:1024
	ds_read_b128 v[180:183], v153 offset:2048
	ds_read_b128 v[184:187], v153 offset:3072
	s_add_u32 s42, s42, 0x40000
	s_addc_u32 s43, s43, 0
	s_mov_b32 m0, s60
	ds_read_b128 v[188:191], v149 offset:32768
	ds_read_b128 v[192:195], v149 offset:33792
	ds_read_b128 v[196:199], v149 offset:34816
	ds_read_b128 v[200:203], v149 offset:35840
	ds_read_b128 v[204:207], v149 offset:36864
	ds_read_b128 v[208:211], v149 offset:37888
	ds_read_b128 v[212:215], v149 offset:38912
	ds_read_b128 v[216:219], v149 offset:39936
	s_nop 0
	global_load_lds_dwordx4 v132, s[42:43]
	s_mov_b32 m0, s61
	s_nop 0
	global_load_lds_dwordx4 v136, s[42:43]
	s_waitcnt vmcnt(8)
	s_waitcnt lgkmcnt(0)
	s_barrier
	s_waitcnt lgkmcnt(0)
	v_mfma_f32_16x16x32_bf16 v[128:131], v[154:157], v[188:191], v[128:131]
	v_mfma_f32_16x16x32_bf16 v[124:127], v[162:165], v[188:191], v[124:127]
	v_mfma_f32_16x16x32_bf16 v[112:115], v[154:157], v[196:199], v[112:115]
	v_mfma_f32_16x16x32_bf16 v[108:111], v[162:165], v[196:199], v[108:111]
	v_mfma_f32_16x16x32_bf16 v[96:99], v[154:157], v[204:207], v[96:99]
	v_mfma_f32_16x16x32_bf16 v[92:95], v[162:165], v[204:207], v[92:95]
	v_mfma_f32_16x16x32_bf16 v[80:83], v[154:157], v[212:215], v[80:83]
	v_mfma_f32_16x16x32_bf16 v[76:79], v[162:165], v[212:215], v[76:79]
	v_mfma_f32_16x16x32_bf16 v[128:131], v[158:161], v[192:195], v[128:131]
	v_mfma_f32_16x16x32_bf16 v[124:127], v[166:169], v[192:195], v[124:127]
	v_mfma_f32_16x16x32_bf16 v[112:115], v[158:161], v[200:203], v[112:115]
	v_mfma_f32_16x16x32_bf16 v[108:111], v[166:169], v[200:203], v[108:111]
	v_mfma_f32_16x16x32_bf16 v[96:99], v[158:161], v[208:211], v[96:99]
	v_mfma_f32_16x16x32_bf16 v[92:95], v[166:169], v[208:211], v[92:95]
	v_mfma_f32_16x16x32_bf16 v[80:83], v[158:161], v[216:219], v[80:83]
	v_mfma_f32_16x16x32_bf16 v[76:79], v[166:169], v[216:219], v[76:79]
	v_mfma_f32_16x16x32_bf16 v[120:123], v[170:173], v[188:191], v[120:123]
	v_mfma_f32_16x16x32_bf16 v[116:119], v[180:183], v[188:191], v[116:119]
	v_mfma_f32_16x16x32_bf16 v[104:107], v[170:173], v[196:199], v[104:107]
	v_mfma_f32_16x16x32_bf16 v[100:103], v[180:183], v[196:199], v[100:103]
	v_mfma_f32_16x16x32_bf16 v[88:91], v[170:173], v[204:207], v[88:91]
	v_mfma_f32_16x16x32_bf16 v[84:87], v[180:183], v[204:207], v[84:87]
	v_mfma_f32_16x16x32_bf16 v[72:75], v[170:173], v[212:215], v[72:75]
	v_mfma_f32_16x16x32_bf16 v[68:71], v[180:183], v[212:215], v[68:71]
	v_mfma_f32_16x16x32_bf16 v[120:123], v[176:179], v[192:195], v[120:123]
	v_mfma_f32_16x16x32_bf16 v[116:119], v[184:187], v[192:195], v[116:119]
	v_mfma_f32_16x16x32_bf16 v[104:107], v[176:179], v[200:203], v[104:107]
	v_mfma_f32_16x16x32_bf16 v[100:103], v[184:187], v[200:203], v[100:103]
	v_mfma_f32_16x16x32_bf16 v[88:91], v[176:179], v[208:211], v[88:91]
	v_mfma_f32_16x16x32_bf16 v[84:87], v[184:187], v[208:211], v[84:87]
	v_mfma_f32_16x16x32_bf16 v[72:75], v[176:179], v[216:219], v[72:75]
	v_mfma_f32_16x16x32_bf16 v[68:71], v[184:187], v[216:219], v[68:71]
	s_barrier
; #define PG8_LDA(dst, b, h) do { _Pragma("unroll") for (int m = 0; m < 4; ++m) _Pragma("unroll") for (int k = 0; k < 2; ++k) dst[m][k] = *(const PG8_LAS bf16x8*)(lds + PG8_SA(b, h) + aoff + m * 2048 + k * 1024); } while (0)
; template <class Epi, class Sched, bool ALIGN_EPI = false, bool SP2 = false>
; __device__ __forceinline__ void gemm_phase(PG8_LAS unsigned char* lds, const Gemm g, const Sched& S, const Epi& E, int wave_s) {
;     ...
;         for (int t = peeled ? 2 : 0; t < nt; t += 2) {
;             const bool last = (t == nt - 2);
;             const char* a1 = cA + (size_t)(t + 1) * kstep;
;             const char* a2 = last ? nA : cA + (size_t)(t + 2) * kstep; const char* b2 = last ? nB : cB + (size_t)(t + 2) * kstep;
;             const char* a3 = a2 + kstep; const char* b3 = b2 + kstep;
;             if (last && has_next) S.a_ready(nxt);
;             if constexpr (SP2) {
;             PG8_SP2_PAIR(PG8_WAIT_V8_STRICT);
;             } else {
;             PG8_LDB(B0, 0, 0); PG8_SCHED; PG8_LDA(At, 0, 0); PG8_STAGE(PG8_SA(1, 1), a1 + hstep, voffA);
;             PG8_WAIT_L(8); PG8_BAR; PG8_WAIT_L(0); PG8_MMA(0, 0, At, B0); PG8_BAR; PG8_SCHED;
;             PG8_LDB(B1, 0, 1); PG8_STAGE(PG8_SB(0, 0), b2, voffB);
;             PG8_BAR; PG8_WAIT_L(0); PG8_MMA(0, 1, At, B1); PG8_BAR;
;             PG8_LDA(At, 0, 1); PG8_STAGE(PG8_SA(0, 0), a2, voffA);
;             PG8_BAR; PG8_WAIT_L(0); PG8_MMA(1, 0, At, B0); PG8_BAR; PG8_SCHED;
;             PG8_STAGE(PG8_SB(0, 1), b2 + hstep, voffB);
;             PG8_WAIT_V(6); PG8_BAR; PG8_MMA(1, 1, At, B1); PG8_BAR;
;             PG8_LDB(B0, 1, 0); PG8_SCHED; PG8_LDA(At, 1, 0); PG8_STAGE(PG8_SA(0, 1), a2 + hstep, voffA);
;             PG8_WAIT_L(8); PG8_BAR; PG8_WAIT_L(0); PG8_MMA(0, 0, At, B0); PG8_BAR; PG8_SCHED;
;             PG8_LDB(B1, 1, 1); PG8_STAGE(PG8_SB(1, 0), b3, voffB);
;             PG8_BAR; PG8_WAIT_L(0); PG8_MMA(0, 1, At, B1); PG8_BAR;
;             PG8_LDA(At, 1, 1); PG8_STAGE(PG8_SA(1, 0), a3, voffA);
;             PG8_BAR; PG8_WAIT_L(0); PG8_MMA(1, 0, At, B0); PG8_BAR; PG8_SCHED;
;             PG8_STAGE(PG8_SB(1, 1), b3 + hstep, voffB);
;             PG8_WAIT_V(6); PG8_BAR; PG8_MMA(1, 1, At, B1); PG8_BAR;
;             }
;         }
;         if constexpr (ALIGN_EPI) { if (wr == 0) PG8_BAR; }
;         if constexpr (!Epi::AFTER_DRAIN) { E(acc, cur, wr, wc, fr, fq, lds, wid); S.done(cur); }
	s_setprio 1
	s_add_u32 s42, s40, 0x80
	s_addc_u32 s43, s41, 0
	s_add_i32 s92, s92, s58
	ds_read_b128 v[188:191], v149 offset:49152
	ds_read_b128 v[192:195], v149 offset:50176
	ds_read_b128 v[196:199], v149 offset:51200
	ds_read_b128 v[200:203], v149 offset:52224
	ds_read_b128 v[204:207], v149 offset:53248
	ds_read_b128 v[208:211], v149 offset:54272
	ds_read_b128 v[212:215], v149 offset:55296
	ds_read_b128 v[216:219], v149 offset:56320
	s_mov_b32 m0, s92
	s_nop 0
	global_load_lds_dwordx4 v134, s[42:43]
	s_mov_b64 s[98:99], s[42:43]
	s_add_i32 s42, s92, 0x2000
	s_add_u32 s40, s40, 0x40080
	s_mov_b32 m0, s42
	s_addc_u32 s41, s41, 0
	s_add_i32 s43, s52, s58
	global_load_lds_dwordx4 v138, s[98:99]
	s_mov_b32 m0, s43
	s_add_i32 s89, s43, 0x2000
	global_load_lds_dwordx4 v134, s[40:41]
	s_mov_b32 m0, s89
	s_nop 0
	global_load_lds_dwordx4 v138, s[40:41]
	s_mov_b32 m0, s63
	s_nop 0
	global_load_lds_dwordx4 v132, s[38:39]
	s_mov_b32 m0, s72
	s_nop 0
	global_load_lds_dwordx4 v136, s[38:39]
	s_setprio 0
	s_waitcnt vmcnt(8)
	s_waitcnt lgkmcnt(0)
	s_barrier
	s_waitcnt lgkmcnt(0)
	v_mfma_f32_16x16x32_bf16 v[64:67], v[154:157], v[188:191], v[64:67]
	v_mfma_f32_16x16x32_bf16 v[60:63], v[162:165], v[188:191], v[60:63]
	v_mfma_f32_16x16x32_bf16 v[48:51], v[154:157], v[196:199], v[48:51]
	v_mfma_f32_16x16x32_bf16 v[44:47], v[162:165], v[196:199], v[44:47]
	v_mfma_f32_16x16x32_bf16 v[32:35], v[154:157], v[204:207], v[32:35]
	v_mfma_f32_16x16x32_bf16 v[28:31], v[162:165], v[204:207], v[28:31]
	v_mfma_f32_16x16x32_bf16 v[16:19], v[154:157], v[212:215], v[16:19]
	v_mfma_f32_16x16x32_bf16 v[12:15], v[162:165], v[212:215], v[12:15]
	v_mfma_f32_16x16x32_bf16 v[64:67], v[158:161], v[192:195], v[64:67]
	v_mfma_f32_16x16x32_bf16 v[60:63], v[166:169], v[192:195], v[60:63]
	v_mfma_f32_16x16x32_bf16 v[48:51], v[158:161], v[200:203], v[48:51]
	v_mfma_f32_16x16x32_bf16 v[44:47], v[166:169], v[200:203], v[44:47]
	v_mfma_f32_16x16x32_bf16 v[32:35], v[158:161], v[208:211], v[32:35]
	v_mfma_f32_16x16x32_bf16 v[28:31], v[166:169], v[208:211], v[28:31]
	v_mfma_f32_16x16x32_bf16 v[16:19], v[158:161], v[216:219], v[16:19]
	v_mfma_f32_16x16x32_bf16 v[12:15], v[166:169], v[216:219], v[12:15]
	v_mfma_f32_16x16x32_bf16 v[56:59], v[170:173], v[188:191], v[56:59]
	v_mfma_f32_16x16x32_bf16 v[52:55], v[180:183], v[188:191], v[52:55]
	v_mfma_f32_16x16x32_bf16 v[40:43], v[170:173], v[196:199], v[40:43]
	v_mfma_f32_16x16x32_bf16 v[36:39], v[180:183], v[196:199], v[36:39]
	v_mfma_f32_16x16x32_bf16 v[24:27], v[170:173], v[204:207], v[24:27]
	v_mfma_f32_16x16x32_bf16 v[20:23], v[180:183], v[204:207], v[20:23]
	v_mfma_f32_16x16x32_bf16 v[6:9], v[170:173], v[212:215], v[8:11]
	v_mfma_f32_16x16x32_bf16 v[2:5], v[180:183], v[212:215], v[2:5]
	v_mfma_f32_16x16x32_bf16 v[56:59], v[176:179], v[192:195], v[56:59]
	v_mfma_f32_16x16x32_bf16 v[52:55], v[184:187], v[192:195], v[52:55]
	v_mfma_f32_16x16x32_bf16 v[40:43], v[176:179], v[200:203], v[40:43]
	v_mfma_f32_16x16x32_bf16 v[36:39], v[184:187], v[200:203], v[36:39]
	v_mfma_f32_16x16x32_bf16 v[24:27], v[176:179], v[208:211], v[24:27]
	v_mfma_f32_16x16x32_bf16 v[20:23], v[184:187], v[208:211], v[20:23]
	v_mfma_f32_16x16x32_bf16 v[8:11], v[176:179], v[216:219], v[6:9]
	v_mfma_f32_16x16x32_bf16 v[4:7], v[184:187], v[216:219], v[2:5]
	s_barrier
	s_add_i32 s96, s96, 2
	s_add_u32 s97, s97, 0x100
	s_addc_u32 vcc_lo, vcc_lo, 0
	s_cmp_gt_u32 s96, 13
	s_mov_b64 s[52:53], s[8:9]
	s_cbranch_scc0 .LBB0_419
	s_and_b64 vcc, exec, s[16:17]
	s_cbranch_vccz .LBB0_422
	v_mbcnt_lo_u32_b32 v188, -1, 0
	v_mbcnt_hi_u32_b32 v188, -1, v188
	v_lshlrev_b32_e32 v188, 2, v188
	v_add_u32_e32 v189, 0x23400, v188
	ds_read_b32 v189, v189
	s_waitcnt lgkmcnt(0)
	v_cmp_gt_u32_e32 vcc, 3, v189
	s_nop 3
	s_and_b32 vcc_lo, vcc_lo, 0xff
	s_cmp_eq_u32 vcc_lo, 0
	s_cbranch_scc1 .Lwok_0
	s_mov_b32 s100, 0
.Lwsl_0:
	v_add_u32_e32 v189, 0x4800, v188
	global_load_dword v189, v189, s[44:45] sc1
	s_waitcnt vmcnt(0)
	v_cmp_gt_u32_e32 vcc, 3, v189
	s_nop 3
	s_and_b32 vcc_lo, vcc_lo, 0xff
	s_cmp_eq_u32 vcc_lo, 0
	s_cbranch_scc1 .Lwok_0
	s_add_u32 s100, s100, 1
	s_cmp_lt_u32 s100, 0x4000
	s_cbranch_scc1 .Lwsl_0
.Lwok_0:
	s_barrier

; template <class Epi, class Sched, bool ALIGN_EPI = false, bool SP2 = false>
; __device__ __forceinline__ void gemm_phase(PG8_LAS unsigned char* lds, const Gemm g, const Sched& S, const Epi& E, int wave_s) {
;     ...
;         for (int t = peeled ? 2 : 0; t < nt; t += 2) {
;             const bool last = (t == nt - 2);
;             const char* a1 = cA + (size_t)(t + 1) * kstep;
;             const char* a2 = last ? nA : cA + (size_t)(t + 2) * kstep; const char* b2 = last ? nB : cB + (size_t)(t + 2) * kstep;
;             const char* a3 = a2 + kstep; const char* b3 = b2 + kstep;
;             if (last && has_next) S.a_ready(nxt);
.Lws_0:
	v_mbcnt_lo_u32_b32 v152, -1, 0
	v_mbcnt_hi_u32_b32 v152, -1, v152
	v_lshlrev_b32_e32 v152, 2, v152
	v_add_u32_e32 v152, 0x4800, v152
	s_mov_b32 m0, 0x23400
	s_nop 0
	global_load_lds_dword v152, s[44:45] sc1
	s_branch .Lwsb_0

; #define PG8_WAIT_V8_STRICT() asm volatile("s_waitcnt vmcnt(8)" ::: "memory")
; template <class Epi, class Sched, bool ALIGN_EPI = false, bool SP2 = false>
; __device__ __forceinline__ void gemm_phase(PG8_LAS unsigned char* lds, const Gemm g, const Sched& S, const Epi& E, int wave_s) {
;     ...
;         for (int t = peeled ? 2 : 0; t < nt; t += 2) {
;             const bool last = (t == nt - 2);
;             const char* a1 = cA + (size_t)(t + 1) * kstep;
;             const char* a2 = last ? nA : cA + (size_t)(t + 2) * kstep; const char* b2 = last ? nB : cB + (size_t)(t + 2) * kstep;
;             const char* a3 = a2 + kstep; const char* b3 = b2 + kstep;
;             if (last && has_next) S.a_ready(nxt);
;             if constexpr (SP2) {
;             PG8_SP2_PAIR(PG8_WAIT_V8_STRICT);
.Lwsb_1:
	v_add_u32_e32 v151, s82, v146
	v_add_u32_e32 v150, s87, v146
	ds_read_b128 v[152:155], v151
	ds_read_b128 v[156:159], v151 offset:1024
	ds_read_b128 v[160:163], v151 offset:2048
	ds_read_b128 v[164:167], v151 offset:3072
	ds_read_b128 v[168:171], v150
	ds_read_b128 v[176:179], v150 offset:1024
	ds_read_b128 v[180:183], v150 offset:2048
	ds_read_b128 v[184:187], v150 offset:3072
	s_add_u32 s30, s40, 0x100
	s_addc_u32 s31, s41, 0
	s_cmp_eq_u32 s95, 12
	s_cselect_b32 s38, s92, s30
	s_cselect_b32 s39, s91, s31
	s_cselect_b32 s36, s94, s96
	s_cselect_b32 s37, s93, s6
	s_add_u32 s34, s38, 0x80
	s_addc_u32 s35, s39, 0
	s_add_u32 s40, s40, 0x40080
	s_addc_u32 s41, s41, 0
	s_add_i32 s90, s72, 0xc000
	ds_read_b128 v[188:191], v149
	ds_read_b128 v[192:195], v149 offset:1024
	ds_read_b128 v[196:199], v149 offset:2048
	ds_read_b128 v[200:203], v149 offset:3072
	ds_read_b128 v[204:207], v149 offset:4096
	ds_read_b128 v[208:211], v149 offset:5120
	ds_read_b128 v[212:215], v149 offset:6144
	ds_read_b128 v[216:219], v149 offset:7168
	s_mov_b32 m0, s90
	s_add_i32 s10, s72, 0xe000
	global_load_lds_dwordx4 v138, s[40:41]
	s_mov_b32 m0, s10
	s_nop 0
	global_load_lds_dwordx4 v134, s[40:41]
	s_waitcnt vmcnt(8)
	s_waitcnt lgkmcnt(0)
	s_barrier
	s_waitcnt lgkmcnt(0)
	v_mfma_f32_16x16x32_bf16 v[124:127], v[152:155], v[188:191], v[124:127]
	v_mfma_f32_16x16x32_bf16 v[116:119], v[160:163], v[188:191], v[116:119]
	v_mfma_f32_16x16x32_bf16 v[108:111], v[152:155], v[196:199], v[108:111]
	v_mfma_f32_16x16x32_bf16 v[100:103], v[160:163], v[196:199], v[100:103]
	v_mfma_f32_16x16x32_bf16 v[92:95], v[152:155], v[204:207], v[92:95]
	v_mfma_f32_16x16x32_bf16 v[84:87], v[160:163], v[204:207], v[84:87]
	v_mfma_f32_16x16x32_bf16 v[76:79], v[152:155], v[212:215], v[76:79]
	v_mfma_f32_16x16x32_bf16 v[60:63], v[160:163], v[212:215], v[60:63]
	v_mfma_f32_16x16x32_bf16 v[124:127], v[156:159], v[192:195], v[124:127]
	v_mfma_f32_16x16x32_bf16 v[116:119], v[164:167], v[192:195], v[116:119]
	v_mfma_f32_16x16x32_bf16 v[108:111], v[156:159], v[200:203], v[108:111]
	v_mfma_f32_16x16x32_bf16 v[100:103], v[164:167], v[200:203], v[100:103]
	v_mfma_f32_16x16x32_bf16 v[92:95], v[156:159], v[208:211], v[92:95]
	v_mfma_f32_16x16x32_bf16 v[84:87], v[164:167], v[208:211], v[84:87]
	v_mfma_f32_16x16x32_bf16 v[76:79], v[156:159], v[216:219], v[76:79]
	v_mfma_f32_16x16x32_bf16 v[60:63], v[164:167], v[216:219], v[60:63]
	v_mfma_f32_16x16x32_bf16 v[128:131], v[168:171], v[188:191], v[128:131]
	v_mfma_f32_16x16x32_bf16 v[120:123], v[180:183], v[188:191], v[120:123]
	v_mfma_f32_16x16x32_bf16 v[112:115], v[168:171], v[196:199], v[112:115]
	v_mfma_f32_16x16x32_bf16 v[104:107], v[180:183], v[196:199], v[104:107]
	v_mfma_f32_16x16x32_bf16 v[96:99], v[168:171], v[204:207], v[96:99]
	v_mfma_f32_16x16x32_bf16 v[88:91], v[180:183], v[204:207], v[88:91]
	v_mfma_f32_16x16x32_bf16 v[80:83], v[168:171], v[212:215], v[80:83]
	v_mfma_f32_16x16x32_bf16 v[68:71], v[180:183], v[212:215], v[68:71]
	v_mfma_f32_16x16x32_bf16 v[128:131], v[176:179], v[192:195], v[128:131]
	v_mfma_f32_16x16x32_bf16 v[120:123], v[184:187], v[192:195], v[120:123]
	v_mfma_f32_16x16x32_bf16 v[112:115], v[176:179], v[200:203], v[112:115]
	v_mfma_f32_16x16x32_bf16 v[104:107], v[184:187], v[200:203], v[104:107]
	v_mfma_f32_16x16x32_bf16 v[96:99], v[176:179], v[208:211], v[96:99]
	v_mfma_f32_16x16x32_bf16 v[88:91], v[184:187], v[208:211], v[88:91]
	v_mfma_f32_16x16x32_bf16 v[80:83], v[176:179], v[216:219], v[80:83]
	v_mfma_f32_16x16x32_bf16 v[68:71], v[184:187], v[216:219], v[68:71]
	s_barrier
	s_setprio 1
	s_mov_b64 s[40:41], s[36:37]
	s_add_i32 s61, s82, s42
	ds_read_b128 v[188:191], v149 offset:16384
	ds_read_b128 v[192:195], v149 offset:17408
	ds_read_b128 v[196:199], v149 offset:18432
	ds_read_b128 v[200:203], v149 offset:19456
	ds_read_b128 v[204:207], v149 offset:20480
	ds_read_b128 v[208:211], v149 offset:21504
	ds_read_b128 v[212:215], v149 offset:22528
	ds_read_b128 v[216:219], v149 offset:23552
	s_mov_b32 m0, s61
	s_add_i32 s21, s61, 0x2000
	global_load_lds_dwordx4 v136, s[40:41]
	s_mov_b64 s[98:99], s[40:41]
	s_add_u32 s40, s36, 0x40000
	s_mov_b32 m0, s21
	s_addc_u32 s41, s37, 0
	s_add_i32 s23, s87, s42
	global_load_lds_dwordx4 v132, s[98:99]
	s_mov_b32 m0, s23
	s_add_i32 s60, s23, 0x2000
	global_load_lds_dwordx4 v136, s[40:41]
	s_mov_b64 s[98:99], s[40:41]
	s_mov_b32 m0, s60
	s_mov_b64 s[40:41], s[38:39]
	global_load_lds_dwordx4 v132, s[98:99]
	s_mov_b32 m0, s72
	s_nop 0
	global_load_lds_dwordx4 v138, s[40:41]
	s_mov_b32 m0, s73
	s_nop 0
	global_load_lds_dwordx4 v134, s[40:41]
	s_setprio 0
	s_waitcnt vmcnt(8)
	s_waitcnt lgkmcnt(0)
	s_barrier
	s_waitcnt lgkmcnt(0)
	v_mfma_f32_16x16x32_bf16 v[64:67], v[152:155], v[188:191], v[64:67]
	v_mfma_f32_16x16x32_bf16 v[52:55], v[160:163], v[188:191], v[52:55]
	v_mfma_f32_16x16x32_bf16 v[44:47], v[152:155], v[196:199], v[44:47]
	v_mfma_f32_16x16x32_bf16 v[36:39], v[160:163], v[196:199], v[36:39]
	v_mfma_f32_16x16x32_bf16 v[28:31], v[152:155], v[204:207], v[28:31]
	v_mfma_f32_16x16x32_bf16 v[20:23], v[160:163], v[204:207], v[20:23]
	v_mfma_f32_16x16x32_bf16 v[12:15], v[152:155], v[212:215], v[12:15]
	v_mfma_f32_16x16x32_bf16 v[2:5], v[160:163], v[212:215], v[4:7]
	v_mfma_f32_16x16x32_bf16 v[64:67], v[156:159], v[192:195], v[64:67]
	v_mfma_f32_16x16x32_bf16 v[52:55], v[164:167], v[192:195], v[52:55]
	v_mfma_f32_16x16x32_bf16 v[44:47], v[156:159], v[200:203], v[44:47]
	v_mfma_f32_16x16x32_bf16 v[36:39], v[164:167], v[200:203], v[36:39]
	v_mfma_f32_16x16x32_bf16 v[28:31], v[156:159], v[208:211], v[28:31]
	v_mfma_f32_16x16x32_bf16 v[20:23], v[164:167], v[208:211], v[20:23]
	v_mfma_f32_16x16x32_bf16 v[12:15], v[156:159], v[216:219], v[12:15]
	v_mfma_f32_16x16x32_bf16 v[2:5], v[164:167], v[216:219], v[2:5]
	v_mfma_f32_16x16x32_bf16 v[72:75], v[168:171], v[188:191], v[72:75]
	v_mfma_f32_16x16x32_bf16 v[56:59], v[180:183], v[188:191], v[56:59]
	v_mfma_f32_16x16x32_bf16 v[48:51], v[168:171], v[196:199], v[48:51]
	v_mfma_f32_16x16x32_bf16 v[40:43], v[180:183], v[196:199], v[40:43]
	v_mfma_f32_16x16x32_bf16 v[32:35], v[168:171], v[204:207], v[32:35]
	v_mfma_f32_16x16x32_bf16 v[24:27], v[180:183], v[204:207], v[24:27]
	v_mfma_f32_16x16x32_bf16 v[16:19], v[168:171], v[212:215], v[16:19]
	v_mfma_f32_16x16x32_bf16 v[6:9], v[180:183], v[212:215], v[8:11]
	v_mfma_f32_16x16x32_bf16 v[72:75], v[176:179], v[192:195], v[72:75]
	v_mfma_f32_16x16x32_bf16 v[56:59], v[184:187], v[192:195], v[56:59]
	v_mfma_f32_16x16x32_bf16 v[48:51], v[176:179], v[200:203], v[48:51]
	v_mfma_f32_16x16x32_bf16 v[40:43], v[184:187], v[200:203], v[40:43]
	v_mfma_f32_16x16x32_bf16 v[32:35], v[176:179], v[208:211], v[32:35]
	v_mfma_f32_16x16x32_bf16 v[24:27], v[184:187], v[208:211], v[24:27]
	v_mfma_f32_16x16x32_bf16 v[16:19], v[176:179], v[216:219], v[16:19]
	v_mfma_f32_16x16x32_bf16 v[8:11], v[184:187], v[216:219], v[6:9]
	s_barrier
	s_add_i32 s7, 0, 0x18000
	s_add_i32 s86, 0, 0x1c000
	v_add_u32_e32 v152, s7, v146
	v_add_u32_e32 v153, s86, v146
	ds_read_b128 v[154:157], v152
	ds_read_b128 v[158:161], v152 offset:1024
	ds_read_b128 v[162:165], v152 offset:2048
	ds_read_b128 v[166:169], v152 offset:3072
	ds_read_b128 v[170:173], v153
	ds_read_b128 v[176:179], v153 offset:1024
	ds_read_b128 v[180:183], v153 offset:2048
	ds_read_b128 v[184:187], v153 offset:3072
	s_add_u32 s38, s38, 0x40000
	s_addc_u32 s39, s39, 0
	s_mov_b32 m0, s74
	ds_read_b128 v[188:191], v149 offset:32768
	ds_read_b128 v[192:195], v149 offset:33792
	ds_read_b128 v[196:199], v149 offset:34816
	ds_read_b128 v[200:203], v149 offset:35840
	ds_read_b128 v[204:207], v149 offset:36864
	ds_read_b128 v[208:211], v149 offset:37888
	ds_read_b128 v[212:215], v149 offset:38912
	ds_read_b128 v[216:219], v149 offset:39936
	s_nop 0
	global_load_lds_dwordx4 v138, s[38:39]
	s_mov_b32 m0, s75
	s_nop 0
	global_load_lds_dwordx4 v134, s[38:39]
	s_waitcnt vmcnt(8)
	s_waitcnt lgkmcnt(0)
	s_barrier
	s_waitcnt lgkmcnt(0)
	v_mfma_f32_16x16x32_bf16 v[124:127], v[154:157], v[188:191], v[124:127]
	v_mfma_f32_16x16x32_bf16 v[116:119], v[162:165], v[188:191], v[116:119]
	v_mfma_f32_16x16x32_bf16 v[108:111], v[154:157], v[196:199], v[108:111]
	v_mfma_f32_16x16x32_bf16 v[100:103], v[162:165], v[196:199], v[100:103]
	v_mfma_f32_16x16x32_bf16 v[92:95], v[154:157], v[204:207], v[92:95]
	v_mfma_f32_16x16x32_bf16 v[84:87], v[162:165], v[204:207], v[84:87]
	v_mfma_f32_16x16x32_bf16 v[76:79], v[154:157], v[212:215], v[76:79]
	v_mfma_f32_16x16x32_bf16 v[60:63], v[162:165], v[212:215], v[60:63]
	v_mfma_f32_16x16x32_bf16 v[124:127], v[158:161], v[192:195], v[124:127]
	v_mfma_f32_16x16x32_bf16 v[116:119], v[166:169], v[192:195], v[116:119]
	v_mfma_f32_16x16x32_bf16 v[108:111], v[158:161], v[200:203], v[108:111]
	v_mfma_f32_16x16x32_bf16 v[100:103], v[166:169], v[200:203], v[100:103]
	v_mfma_f32_16x16x32_bf16 v[92:95], v[158:161], v[208:211], v[92:95]
	v_mfma_f32_16x16x32_bf16 v[84:87], v[166:169], v[208:211], v[84:87]
	v_mfma_f32_16x16x32_bf16 v[76:79], v[158:161], v[216:219], v[76:79]
	v_mfma_f32_16x16x32_bf16 v[60:63], v[166:169], v[216:219], v[60:63]
	v_mfma_f32_16x16x32_bf16 v[128:131], v[170:173], v[188:191], v[128:131]
	v_mfma_f32_16x16x32_bf16 v[120:123], v[180:183], v[188:191], v[120:123]
	v_mfma_f32_16x16x32_bf16 v[112:115], v[170:173], v[196:199], v[112:115]
	v_mfma_f32_16x16x32_bf16 v[104:107], v[180:183], v[196:199], v[104:107]
	v_mfma_f32_16x16x32_bf16 v[96:99], v[170:173], v[204:207], v[96:99]
	v_mfma_f32_16x16x32_bf16 v[88:91], v[180:183], v[204:207], v[88:91]
	v_mfma_f32_16x16x32_bf16 v[80:83], v[170:173], v[212:215], v[80:83]
	v_mfma_f32_16x16x32_bf16 v[68:71], v[180:183], v[212:215], v[68:71]
	v_mfma_f32_16x16x32_bf16 v[128:131], v[176:179], v[192:195], v[128:131]
	v_mfma_f32_16x16x32_bf16 v[120:123], v[184:187], v[192:195], v[120:123]
	v_mfma_f32_16x16x32_bf16 v[112:115], v[176:179], v[200:203], v[112:115]
	v_mfma_f32_16x16x32_bf16 v[104:107], v[184:187], v[200:203], v[104:107]
	v_mfma_f32_16x16x32_bf16 v[96:99], v[176:179], v[208:211], v[96:99]
	v_mfma_f32_16x16x32_bf16 v[88:91], v[184:187], v[208:211], v[88:91]
	v_mfma_f32_16x16x32_bf16 v[80:83], v[176:179], v[216:219], v[80:83]
	v_mfma_f32_16x16x32_bf16 v[68:71], v[184:187], v[216:219], v[68:71]
	s_barrier
; #define PG8_LDA(dst, b, h) do { _Pragma("unroll") for (int m = 0; m < 4; ++m) _Pragma("unroll") for (int k = 0; k < 2; ++k) dst[m][k] = *(const PG8_LAS bf16x8*)(lds + PG8_SA(b, h) + aoff + m * 2048 + k * 1024); } while (0)
; template <class Epi, class Sched, bool ALIGN_EPI = false, bool SP2 = false>
; __device__ __forceinline__ void gemm_phase(PG8_LAS unsigned char* lds, const Gemm g, const Sched& S, const Epi& E, int wave_s) {
;     ...
;         for (int t = peeled ? 2 : 0; t < nt; t += 2) {
;             const bool last = (t == nt - 2);
;             const char* a1 = cA + (size_t)(t + 1) * kstep;
;             const char* a2 = last ? nA : cA + (size_t)(t + 2) * kstep; const char* b2 = last ? nB : cB + (size_t)(t + 2) * kstep;
;             const char* a3 = a2 + kstep; const char* b3 = b2 + kstep;
;             if (last && has_next) S.a_ready(nxt);
;             if constexpr (SP2) {
;             PG8_SP2_PAIR(PG8_WAIT_V8_STRICT);
;             } else {
;             PG8_LDB(B0, 0, 0); PG8_SCHED; PG8_LDA(At, 0, 0); PG8_STAGE(PG8_SA(1, 1), a1 + hstep, voffA);
;             PG8_WAIT_L(8); PG8_BAR; PG8_WAIT_L(0); PG8_MMA(0, 0, At, B0); PG8_BAR; PG8_SCHED;
;             PG8_LDB(B1, 0, 1); PG8_STAGE(PG8_SB(0, 0), b2, voffB);
;             PG8_BAR; PG8_WAIT_L(0); PG8_MMA(0, 1, At, B1); PG8_BAR;
;             PG8_LDA(At, 0, 1); PG8_STAGE(PG8_SA(0, 0), a2, voffA);
;             PG8_BAR; PG8_WAIT_L(0); PG8_MMA(1, 0, At, B0); PG8_BAR; PG8_SCHED;
;             PG8_STAGE(PG8_SB(0, 1), b2 + hstep, voffB);
;             PG8_WAIT_V(6); PG8_BAR; PG8_MMA(1, 1, At, B1); PG8_BAR;
;             PG8_LDB(B0, 1, 0); PG8_SCHED; PG8_LDA(At, 1, 0); PG8_STAGE(PG8_SA(0, 1), a2 + hstep, voffA);
;             PG8_WAIT_L(8); PG8_BAR; PG8_WAIT_L(0); PG8_MMA(0, 0, At, B0); PG8_BAR; PG8_SCHED;
;             PG8_LDB(B1, 1, 1); PG8_STAGE(PG8_SB(1, 0), b3, voffB);
;             PG8_BAR; PG8_WAIT_L(0); PG8_MMA(0, 1, At, B1); PG8_BAR;
;             PG8_LDA(At, 1, 1); PG8_STAGE(PG8_SA(1, 0), a3, voffA);
;             PG8_BAR; PG8_WAIT_L(0); PG8_MMA(1, 0, At, B0); PG8_BAR; PG8_SCHED;
;             PG8_STAGE(PG8_SB(1, 1), b3 + hstep, voffB);
;             PG8_WAIT_V(6); PG8_BAR; PG8_MMA(1, 1, At, B1); PG8_BAR;
;             }
;         }
;         if constexpr (ALIGN_EPI) { if (wr == 0) PG8_BAR; }
;         if constexpr (!Epi::AFTER_DRAIN) { E(acc, cur, wr, wc, fr, fq, lds, wid); S.done(cur); }
	s_setprio 1
	s_add_u32 s40, s36, 0x80
	s_addc_u32 s41, s37, 0
	s_add_i32 s39, s7, s42
	ds_read_b128 v[188:191], v149 offset:49152
	ds_read_b128 v[192:195], v149 offset:50176
	ds_read_b128 v[196:199], v149 offset:51200
	ds_read_b128 v[200:203], v149 offset:52224
	ds_read_b128 v[204:207], v149 offset:53248
	ds_read_b128 v[208:211], v149 offset:54272
	ds_read_b128 v[212:215], v149 offset:55296
	ds_read_b128 v[216:219], v149 offset:56320
	s_mov_b32 m0, s39
	s_add_i32 s38, s39, 0x2000
	global_load_lds_dwordx4 v136, s[40:41]
	s_mov_b64 s[98:99], s[40:41]
	s_add_u32 s40, s36, 0x40080
	s_mov_b32 m0, s38
	s_addc_u32 s41, s37, 0
	s_add_i32 s36, s86, s42
	global_load_lds_dwordx4 v132, s[98:99]
	s_mov_b32 m0, s36
	s_add_i32 s37, s36, 0x2000
	global_load_lds_dwordx4 v136, s[40:41]
	s_mov_b32 m0, s37
	s_nop 0
	global_load_lds_dwordx4 v132, s[40:41]
	s_mov_b32 m0, s76
	s_nop 0
	global_load_lds_dwordx4 v138, s[34:35]
	s_mov_b32 m0, s77
	s_nop 0
	global_load_lds_dwordx4 v134, s[34:35]
	s_setprio 0
	s_waitcnt vmcnt(8)
	s_waitcnt lgkmcnt(0)
	s_barrier
	s_waitcnt lgkmcnt(0)
	v_mfma_f32_16x16x32_bf16 v[64:67], v[154:157], v[188:191], v[64:67]
	v_mfma_f32_16x16x32_bf16 v[52:55], v[162:165], v[188:191], v[52:55]
	v_mfma_f32_16x16x32_bf16 v[44:47], v[154:157], v[196:199], v[44:47]
	v_mfma_f32_16x16x32_bf16 v[36:39], v[162:165], v[196:199], v[36:39]
	v_mfma_f32_16x16x32_bf16 v[28:31], v[154:157], v[204:207], v[28:31]
	v_mfma_f32_16x16x32_bf16 v[20:23], v[162:165], v[204:207], v[20:23]
	v_mfma_f32_16x16x32_bf16 v[12:15], v[154:157], v[212:215], v[12:15]
	v_mfma_f32_16x16x32_bf16 v[2:5], v[162:165], v[212:215], v[2:5]
	v_mfma_f32_16x16x32_bf16 v[64:67], v[158:161], v[192:195], v[64:67]
	v_mfma_f32_16x16x32_bf16 v[52:55], v[166:169], v[192:195], v[52:55]
	v_mfma_f32_16x16x32_bf16 v[44:47], v[158:161], v[200:203], v[44:47]
	v_mfma_f32_16x16x32_bf16 v[36:39], v[166:169], v[200:203], v[36:39]
	v_mfma_f32_16x16x32_bf16 v[28:31], v[158:161], v[208:211], v[28:31]
	v_mfma_f32_16x16x32_bf16 v[20:23], v[166:169], v[208:211], v[20:23]
	v_mfma_f32_16x16x32_bf16 v[12:15], v[158:161], v[216:219], v[12:15]
	v_mfma_f32_16x16x32_bf16 v[4:7], v[166:169], v[216:219], v[2:5]
	v_mfma_f32_16x16x32_bf16 v[72:75], v[170:173], v[188:191], v[72:75]
	v_mfma_f32_16x16x32_bf16 v[56:59], v[180:183], v[188:191], v[56:59]
	v_mfma_f32_16x16x32_bf16 v[48:51], v[170:173], v[196:199], v[48:51]
	v_mfma_f32_16x16x32_bf16 v[40:43], v[180:183], v[196:199], v[40:43]
	v_mfma_f32_16x16x32_bf16 v[32:35], v[170:173], v[204:207], v[32:35]
	v_mfma_f32_16x16x32_bf16 v[24:27], v[180:183], v[204:207], v[24:27]
	v_mfma_f32_16x16x32_bf16 v[16:19], v[170:173], v[212:215], v[16:19]
	v_mfma_f32_16x16x32_bf16 v[8:11], v[180:183], v[212:215], v[8:11]
	v_mfma_f32_16x16x32_bf16 v[72:75], v[176:179], v[192:195], v[72:75]
	v_mfma_f32_16x16x32_bf16 v[56:59], v[184:187], v[192:195], v[56:59]
	v_mfma_f32_16x16x32_bf16 v[48:51], v[176:179], v[200:203], v[48:51]
	v_mfma_f32_16x16x32_bf16 v[40:43], v[184:187], v[200:203], v[40:43]
	v_mfma_f32_16x16x32_bf16 v[32:35], v[176:179], v[208:211], v[32:35]
	v_mfma_f32_16x16x32_bf16 v[24:27], v[184:187], v[208:211], v[24:27]
	v_mfma_f32_16x16x32_bf16 v[16:19], v[176:179], v[216:219], v[16:19]
	v_mfma_f32_16x16x32_bf16 v[8:11], v[184:187], v[216:219], v[8:11]
	s_barrier
	s_add_i32 s95, s95, 2
	s_add_u32 s96, s96, 0x100
	s_addc_u32 s6, s6, 0
	s_cmp_gt_u32 s95, 13
	s_mov_b64 s[40:41], s[30:31]
	s_cbranch_scc0 .LBB0_912
	s_and_b64 vcc, exec, s[18:19]
	s_cbranch_vccz .LBB0_915
	v_mbcnt_lo_u32_b32 v188, -1, 0
	v_mbcnt_hi_u32_b32 v188, -1, v188
	v_lshlrev_b32_e32 v188, 2, v188
	v_add_u32_e32 v189, 0x23400, v188
	ds_read_b32 v189, v189
	s_waitcnt lgkmcnt(0)
	v_cmp_gt_u32_e32 vcc, 6, v189
	s_nop 3
	s_and_b32 vcc_lo, vcc_lo, 0xff
	s_cmp_eq_u32 vcc_lo, 0
	s_cbranch_scc1 .Lwok_1
	s_mov_b32 s100, 0
.Lwsl_1:
	v_add_u32_e32 v189, 0x4800, v188
	global_load_dword v189, v189, s[44:45] sc1
	s_waitcnt vmcnt(0)
	v_cmp_gt_u32_e32 vcc, 6, v189
	s_nop 3
	s_and_b32 vcc_lo, vcc_lo, 0xff
	s_cmp_eq_u32 vcc_lo, 0
	s_cbranch_scc1 .Lwok_1
	s_add_u32 s100, s100, 1
	s_cmp_lt_u32 s100, 0x4000
	s_cbranch_scc1 .Lwsl_1

; #define PG8_WAIT_V8_STRICT() asm volatile("s_waitcnt vmcnt(8)" ::: "memory")
; template <class Epi, class Sched, bool ALIGN_EPI = false, bool SP2 = false>
; __device__ __forceinline__ void gemm_phase(PG8_LAS unsigned char* lds, const Gemm g, const Sched& S, const Epi& E, int wave_s) {
;     ...
;         for (int t = peeled ? 2 : 0; t < nt; t += 2) {
;             const bool last = (t == nt - 2);
;             const char* a1 = cA + (size_t)(t + 1) * kstep;
;             const char* a2 = last ? nA : cA + (size_t)(t + 2) * kstep; const char* b2 = last ? nB : cB + (size_t)(t + 2) * kstep;
;             const char* a3 = a2 + kstep; const char* b3 = b2 + kstep;
;             if (last && has_next) S.a_ready(nxt);
;             if constexpr (SP2) {
;             PG8_SP2_PAIR(PG8_WAIT_V8_STRICT);
.Lwsb_2:
	v_add_u32_e32 v151, s59, v146
	v_add_u32_e32 v150, s60, v146
	ds_read_b128 v[152:155], v151
	ds_read_b128 v[156:159], v151 offset:1024
	ds_read_b128 v[160:163], v151 offset:2048
	ds_read_b128 v[164:167], v151 offset:3072
	ds_read_b128 v[168:171], v150
	ds_read_b128 v[172:175], v150 offset:1024
	ds_read_b128 v[176:179], v150 offset:2048
	ds_read_b128 v[180:183], v150 offset:3072
	s_add_u32 s24, s34, 0x100
	s_addc_u32 s25, s35, 0
	s_cmp_eq_u32 s70, 12
	s_cselect_b32 s30, s67, s24
	s_cselect_b32 s31, s66, s25
	s_cselect_b32 s28, s69, s71
	s_cselect_b32 s29, s68, s72
	s_add_u32 s26, s30, 0x80
	s_addc_u32 s27, s31, 0
	s_add_u32 s34, s34, 0x40080
	s_addc_u32 s35, s35, 0
	s_add_i32 s65, s42, 0xc000
	ds_read_b128 v[184:187], v149
	ds_read_b128 v[188:191], v149 offset:1024
	ds_read_b128 v[192:195], v149 offset:2048
	ds_read_b128 v[196:199], v149 offset:3072
	ds_read_b128 v[200:203], v149 offset:4096
	ds_read_b128 v[204:207], v149 offset:5120
	ds_read_b128 v[208:211], v149 offset:6144
	ds_read_b128 v[212:215], v149 offset:7168
	s_mov_b32 m0, s65
	s_add_i32 s8, s42, 0xe000
	global_load_lds_dwordx4 v138, s[34:35]
	s_mov_b32 m0, s8
	s_nop 0
	global_load_lds_dwordx4 v134, s[34:35]
	s_waitcnt vmcnt(8)
	s_waitcnt lgkmcnt(0)
	s_barrier
	s_waitcnt lgkmcnt(0)
	v_mfma_f32_16x16x32_bf16 v[124:127], v[152:155], v[184:187], v[124:127]
	v_mfma_f32_16x16x32_bf16 v[116:119], v[160:163], v[184:187], v[116:119]
	v_mfma_f32_16x16x32_bf16 v[108:111], v[152:155], v[192:195], v[108:111]
	v_mfma_f32_16x16x32_bf16 v[100:103], v[160:163], v[192:195], v[100:103]
	v_mfma_f32_16x16x32_bf16 v[92:95], v[152:155], v[200:203], v[92:95]
	v_mfma_f32_16x16x32_bf16 v[84:87], v[160:163], v[200:203], v[84:87]
	v_mfma_f32_16x16x32_bf16 v[76:79], v[152:155], v[208:211], v[76:79]
	v_mfma_f32_16x16x32_bf16 v[60:63], v[160:163], v[208:211], v[60:63]
	v_mfma_f32_16x16x32_bf16 v[124:127], v[156:159], v[188:191], v[124:127]
	v_mfma_f32_16x16x32_bf16 v[116:119], v[164:167], v[188:191], v[116:119]
	v_mfma_f32_16x16x32_bf16 v[108:111], v[156:159], v[196:199], v[108:111]
	v_mfma_f32_16x16x32_bf16 v[100:103], v[164:167], v[196:199], v[100:103]
	v_mfma_f32_16x16x32_bf16 v[92:95], v[156:159], v[204:207], v[92:95]
	v_mfma_f32_16x16x32_bf16 v[84:87], v[164:167], v[204:207], v[84:87]
	v_mfma_f32_16x16x32_bf16 v[76:79], v[156:159], v[212:215], v[76:79]
	v_mfma_f32_16x16x32_bf16 v[60:63], v[164:167], v[212:215], v[60:63]
	v_mfma_f32_16x16x32_bf16 v[128:131], v[168:171], v[184:187], v[128:131]
	v_mfma_f32_16x16x32_bf16 v[120:123], v[176:179], v[184:187], v[120:123]
	v_mfma_f32_16x16x32_bf16 v[112:115], v[168:171], v[192:195], v[112:115]
	v_mfma_f32_16x16x32_bf16 v[104:107], v[176:179], v[192:195], v[104:107]
	v_mfma_f32_16x16x32_bf16 v[96:99], v[168:171], v[200:203], v[96:99]
	v_mfma_f32_16x16x32_bf16 v[88:91], v[176:179], v[200:203], v[88:91]
	v_mfma_f32_16x16x32_bf16 v[80:83], v[168:171], v[208:211], v[80:83]
	v_mfma_f32_16x16x32_bf16 v[68:71], v[176:179], v[208:211], v[68:71]
	v_mfma_f32_16x16x32_bf16 v[128:131], v[172:175], v[188:191], v[128:131]
	v_mfma_f32_16x16x32_bf16 v[120:123], v[180:183], v[188:191], v[120:123]
	v_mfma_f32_16x16x32_bf16 v[112:115], v[172:175], v[196:199], v[112:115]
	v_mfma_f32_16x16x32_bf16 v[104:107], v[180:183], v[196:199], v[104:107]
	v_mfma_f32_16x16x32_bf16 v[96:99], v[172:175], v[204:207], v[96:99]
	v_mfma_f32_16x16x32_bf16 v[88:91], v[180:183], v[204:207], v[88:91]
	v_mfma_f32_16x16x32_bf16 v[80:83], v[172:175], v[212:215], v[80:83]
	v_mfma_f32_16x16x32_bf16 v[68:71], v[180:183], v[212:215], v[68:71]
	s_barrier
	s_setprio 1
	s_mov_b64 s[34:35], s[28:29]
	s_add_i32 s64, s59, s38
	ds_read_b128 v[184:187], v149 offset:16384
	ds_read_b128 v[188:191], v149 offset:17408
	ds_read_b128 v[192:195], v149 offset:18432
	ds_read_b128 v[196:199], v149 offset:19456
	ds_read_b128 v[200:203], v149 offset:20480
	ds_read_b128 v[204:207], v149 offset:21504
	ds_read_b128 v[208:211], v149 offset:22528
	ds_read_b128 v[212:215], v149 offset:23552
	s_mov_b32 m0, s64
	s_add_i32 s15, s64, 0x2000
	global_load_lds_dwordx4 v136, s[34:35]
	s_mov_b64 s[98:99], s[34:35]
	s_add_u32 s34, s28, 0x40000
	s_mov_b32 m0, s15
	s_addc_u32 s35, s29, 0
	s_add_i32 s17, s60, s38
	global_load_lds_dwordx4 v132, s[98:99]
	s_mov_b32 m0, s17
	s_add_i32 s63, s17, 0x2000
	global_load_lds_dwordx4 v136, s[34:35]
	s_mov_b64 s[98:99], s[34:35]
	s_mov_b32 m0, s63
	s_mov_b64 s[34:35], s[30:31]
	global_load_lds_dwordx4 v132, s[98:99]
	s_mov_b32 m0, s42
	s_nop 0
	global_load_lds_dwordx4 v138, s[34:35]
	s_mov_b32 m0, s43
	s_nop 0
	global_load_lds_dwordx4 v134, s[34:35]
	s_setprio 0
	s_waitcnt vmcnt(8)
	s_waitcnt lgkmcnt(0)
	s_barrier
	s_waitcnt lgkmcnt(0)
	v_mfma_f32_16x16x32_bf16 v[64:67], v[152:155], v[184:187], v[64:67]
	v_mfma_f32_16x16x32_bf16 v[52:55], v[160:163], v[184:187], v[52:55]
	v_mfma_f32_16x16x32_bf16 v[44:47], v[152:155], v[192:195], v[44:47]
	v_mfma_f32_16x16x32_bf16 v[36:39], v[160:163], v[192:195], v[36:39]
	v_mfma_f32_16x16x32_bf16 v[28:31], v[152:155], v[200:203], v[28:31]
	v_mfma_f32_16x16x32_bf16 v[20:23], v[160:163], v[200:203], v[20:23]
	v_mfma_f32_16x16x32_bf16 v[12:15], v[152:155], v[208:211], v[12:15]
	v_mfma_f32_16x16x32_bf16 v[2:5], v[160:163], v[208:211], v[4:7]
	v_mfma_f32_16x16x32_bf16 v[64:67], v[156:159], v[188:191], v[64:67]
	v_mfma_f32_16x16x32_bf16 v[52:55], v[164:167], v[188:191], v[52:55]
	v_mfma_f32_16x16x32_bf16 v[44:47], v[156:159], v[196:199], v[44:47]
	v_mfma_f32_16x16x32_bf16 v[36:39], v[164:167], v[196:199], v[36:39]
	v_mfma_f32_16x16x32_bf16 v[28:31], v[156:159], v[204:207], v[28:31]
	v_mfma_f32_16x16x32_bf16 v[20:23], v[164:167], v[204:207], v[20:23]
	v_mfma_f32_16x16x32_bf16 v[12:15], v[156:159], v[212:215], v[12:15]
	v_mfma_f32_16x16x32_bf16 v[2:5], v[164:167], v[212:215], v[2:5]
	v_mfma_f32_16x16x32_bf16 v[72:75], v[168:171], v[184:187], v[72:75]
	v_mfma_f32_16x16x32_bf16 v[56:59], v[176:179], v[184:187], v[56:59]
	v_mfma_f32_16x16x32_bf16 v[48:51], v[168:171], v[192:195], v[48:51]
	v_mfma_f32_16x16x32_bf16 v[40:43], v[176:179], v[192:195], v[40:43]
	v_mfma_f32_16x16x32_bf16 v[32:35], v[168:171], v[200:203], v[32:35]
	v_mfma_f32_16x16x32_bf16 v[24:27], v[176:179], v[200:203], v[24:27]
	v_mfma_f32_16x16x32_bf16 v[16:19], v[168:171], v[208:211], v[16:19]
	v_mfma_f32_16x16x32_bf16 v[6:9], v[176:179], v[208:211], v[8:11]
	v_mfma_f32_16x16x32_bf16 v[72:75], v[172:175], v[188:191], v[72:75]
	v_mfma_f32_16x16x32_bf16 v[56:59], v[180:183], v[188:191], v[56:59]
	v_mfma_f32_16x16x32_bf16 v[48:51], v[172:175], v[196:199], v[48:51]
	v_mfma_f32_16x16x32_bf16 v[40:43], v[180:183], v[196:199], v[40:43]
	v_mfma_f32_16x16x32_bf16 v[32:35], v[172:175], v[204:207], v[32:35]
	v_mfma_f32_16x16x32_bf16 v[24:27], v[180:183], v[204:207], v[24:27]
	v_mfma_f32_16x16x32_bf16 v[16:19], v[172:175], v[212:215], v[16:19]
	v_mfma_f32_16x16x32_bf16 v[8:11], v[180:183], v[212:215], v[6:9]
	s_barrier
	s_add_i32 s73, 0, 0x18000
	s_add_i32 s74, 0, 0x1c000
	v_add_u32_e32 v152, s73, v146
	v_add_u32_e32 v153, s74, v146
	ds_read_b128 v[154:157], v152
	ds_read_b128 v[158:161], v152 offset:1024
	ds_read_b128 v[162:165], v152 offset:2048
	ds_read_b128 v[166:169], v152 offset:3072
	ds_read_b128 v[170:173], v153
	ds_read_b128 v[174:177], v153 offset:1024
	ds_read_b128 v[178:181], v153 offset:2048
	ds_read_b128 v[182:185], v153 offset:3072
	s_add_u32 s30, s30, 0x40000
	s_addc_u32 s31, s31, 0
	s_mov_b32 m0, s52
	ds_read_b128 v[186:189], v149 offset:32768
	ds_read_b128 v[190:193], v149 offset:33792
	ds_read_b128 v[194:197], v149 offset:34816
	ds_read_b128 v[198:201], v149 offset:35840
	ds_read_b128 v[202:205], v149 offset:36864
	ds_read_b128 v[206:209], v149 offset:37888
	ds_read_b128 v[210:213], v149 offset:38912
	ds_read_b128 v[214:217], v149 offset:39936
	s_nop 0
	global_load_lds_dwordx4 v138, s[30:31]
	s_mov_b32 m0, s53
	s_nop 0
	global_load_lds_dwordx4 v134, s[30:31]
	s_waitcnt vmcnt(8)
	s_waitcnt lgkmcnt(0)
	s_barrier
	s_waitcnt lgkmcnt(0)
	v_mfma_f32_16x16x32_bf16 v[124:127], v[154:157], v[186:189], v[124:127]
	v_mfma_f32_16x16x32_bf16 v[116:119], v[162:165], v[186:189], v[116:119]
	v_mfma_f32_16x16x32_bf16 v[108:111], v[154:157], v[194:197], v[108:111]
	v_mfma_f32_16x16x32_bf16 v[100:103], v[162:165], v[194:197], v[100:103]
	v_mfma_f32_16x16x32_bf16 v[92:95], v[154:157], v[202:205], v[92:95]
	v_mfma_f32_16x16x32_bf16 v[84:87], v[162:165], v[202:205], v[84:87]
	v_mfma_f32_16x16x32_bf16 v[76:79], v[154:157], v[210:213], v[76:79]
	v_mfma_f32_16x16x32_bf16 v[60:63], v[162:165], v[210:213], v[60:63]
	v_mfma_f32_16x16x32_bf16 v[124:127], v[158:161], v[190:193], v[124:127]
	v_mfma_f32_16x16x32_bf16 v[116:119], v[166:169], v[190:193], v[116:119]
	v_mfma_f32_16x16x32_bf16 v[108:111], v[158:161], v[198:201], v[108:111]
	v_mfma_f32_16x16x32_bf16 v[100:103], v[166:169], v[198:201], v[100:103]
	v_mfma_f32_16x16x32_bf16 v[92:95], v[158:161], v[206:209], v[92:95]
	v_mfma_f32_16x16x32_bf16 v[84:87], v[166:169], v[206:209], v[84:87]
	v_mfma_f32_16x16x32_bf16 v[76:79], v[158:161], v[214:217], v[76:79]
	v_mfma_f32_16x16x32_bf16 v[60:63], v[166:169], v[214:217], v[60:63]
	v_mfma_f32_16x16x32_bf16 v[128:131], v[170:173], v[186:189], v[128:131]
	v_mfma_f32_16x16x32_bf16 v[120:123], v[178:181], v[186:189], v[120:123]
	v_mfma_f32_16x16x32_bf16 v[112:115], v[170:173], v[194:197], v[112:115]
	v_mfma_f32_16x16x32_bf16 v[104:107], v[178:181], v[194:197], v[104:107]
	v_mfma_f32_16x16x32_bf16 v[96:99], v[170:173], v[202:205], v[96:99]
	v_mfma_f32_16x16x32_bf16 v[88:91], v[178:181], v[202:205], v[88:91]
	v_mfma_f32_16x16x32_bf16 v[80:83], v[170:173], v[210:213], v[80:83]
	v_mfma_f32_16x16x32_bf16 v[68:71], v[178:181], v[210:213], v[68:71]
	v_mfma_f32_16x16x32_bf16 v[128:131], v[174:177], v[190:193], v[128:131]
	v_mfma_f32_16x16x32_bf16 v[120:123], v[182:185], v[190:193], v[120:123]
	v_mfma_f32_16x16x32_bf16 v[112:115], v[174:177], v[198:201], v[112:115]
	v_mfma_f32_16x16x32_bf16 v[104:107], v[182:185], v[198:201], v[104:107]
	v_mfma_f32_16x16x32_bf16 v[96:99], v[174:177], v[206:209], v[96:99]
	v_mfma_f32_16x16x32_bf16 v[88:91], v[182:185], v[206:209], v[88:91]
	v_mfma_f32_16x16x32_bf16 v[80:83], v[174:177], v[214:217], v[80:83]
	v_mfma_f32_16x16x32_bf16 v[68:71], v[182:185], v[214:217], v[68:71]
	s_barrier
; #define PG8_LDA(dst, b, h) do { _Pragma("unroll") for (int m = 0; m < 4; ++m) _Pragma("unroll") for (int k = 0; k < 2; ++k) dst[m][k] = *(const PG8_LAS bf16x8*)(lds + PG8_SA(b, h) + aoff + m * 2048 + k * 1024); } while (0)
; template <class Epi, class Sched, bool ALIGN_EPI = false, bool SP2 = false>
; __device__ __forceinline__ void gemm_phase(PG8_LAS unsigned char* lds, const Gemm g, const Sched& S, const Epi& E, int wave_s) {
;     ...
;         for (int t = peeled ? 2 : 0; t < nt; t += 2) {
;             const bool last = (t == nt - 2);
;             const char* a1 = cA + (size_t)(t + 1) * kstep;
;             const char* a2 = last ? nA : cA + (size_t)(t + 2) * kstep; const char* b2 = last ? nB : cB + (size_t)(t + 2) * kstep;
;             const char* a3 = a2 + kstep; const char* b3 = b2 + kstep;
;             if (last && has_next) S.a_ready(nxt);
;             if constexpr (SP2) {
;             PG8_SP2_PAIR(PG8_WAIT_V8_STRICT);
;             } else {
;             PG8_LDB(B0, 0, 0); PG8_SCHED; PG8_LDA(At, 0, 0); PG8_STAGE(PG8_SA(1, 1), a1 + hstep, voffA);
;             PG8_WAIT_L(8); PG8_BAR; PG8_WAIT_L(0); PG8_MMA(0, 0, At, B0); PG8_BAR; PG8_SCHED;
;             PG8_LDB(B1, 0, 1); PG8_STAGE(PG8_SB(0, 0), b2, voffB);
;             PG8_BAR; PG8_WAIT_L(0); PG8_MMA(0, 1, At, B1); PG8_BAR;
;             PG8_LDA(At, 0, 1); PG8_STAGE(PG8_SA(0, 0), a2, voffA);
;             PG8_BAR; PG8_WAIT_L(0); PG8_MMA(1, 0, At, B0); PG8_BAR; PG8_SCHED;
;             PG8_STAGE(PG8_SB(0, 1), b2 + hstep, voffB);
;             PG8_WAIT_V(6); PG8_BAR; PG8_MMA(1, 1, At, B1); PG8_BAR;
;             PG8_LDB(B0, 1, 0); PG8_SCHED; PG8_LDA(At, 1, 0); PG8_STAGE(PG8_SA(0, 1), a2 + hstep, voffA);
;             PG8_WAIT_L(8); PG8_BAR; PG8_WAIT_L(0); PG8_MMA(0, 0, At, B0); PG8_BAR; PG8_SCHED;
;             PG8_LDB(B1, 1, 1); PG8_STAGE(PG8_SB(1, 0), b3, voffB);
;             PG8_BAR; PG8_WAIT_L(0); PG8_MMA(0, 1, At, B1); PG8_BAR;
;             PG8_LDA(At, 1, 1); PG8_STAGE(PG8_SA(1, 0), a3, voffA);
;             PG8_BAR; PG8_WAIT_L(0); PG8_MMA(1, 0, At, B0); PG8_BAR; PG8_SCHED;
;             PG8_STAGE(PG8_SB(1, 1), b3 + hstep, voffB);
;             PG8_WAIT_V(6); PG8_BAR; PG8_MMA(1, 1, At, B1); PG8_BAR;
;             }
;         }
;         if constexpr (ALIGN_EPI) { if (wr == 0) PG8_BAR; }
;         if constexpr (!Epi::AFTER_DRAIN) { E(acc, cur, wr, wc, fr, fq, lds, wid); S.done(cur); }
	s_setprio 1
	s_add_u32 s34, s28, 0x80
	s_addc_u32 s35, s29, 0
	s_add_i32 s31, s73, s38
	ds_read_b128 v[186:189], v149 offset:49152
	ds_read_b128 v[190:193], v149 offset:50176
	ds_read_b128 v[194:197], v149 offset:51200
	ds_read_b128 v[198:201], v149 offset:52224
	ds_read_b128 v[202:205], v149 offset:53248
	ds_read_b128 v[206:209], v149 offset:54272
	ds_read_b128 v[210:213], v149 offset:55296
	ds_read_b128 v[214:217], v149 offset:56320
	s_mov_b32 m0, s31
	s_add_i32 s30, s31, 0x2000
	global_load_lds_dwordx4 v136, s[34:35]
	s_mov_b64 s[98:99], s[34:35]
	s_add_u32 s34, s28, 0x40080
	s_mov_b32 m0, s30
	s_addc_u32 s35, s29, 0
	s_add_i32 s28, s74, s38
	global_load_lds_dwordx4 v132, s[98:99]
	s_mov_b32 m0, s28
	s_add_i32 s29, s28, 0x2000
	global_load_lds_dwordx4 v136, s[34:35]
	s_mov_b32 m0, s29
	s_nop 0
	global_load_lds_dwordx4 v132, s[34:35]
	s_mov_b32 m0, s54
	s_nop 0
	global_load_lds_dwordx4 v138, s[26:27]
	s_mov_b32 m0, s55
	s_nop 0
	global_load_lds_dwordx4 v134, s[26:27]
	s_setprio 0
	s_waitcnt vmcnt(8)
	s_waitcnt lgkmcnt(0)
	s_barrier
	s_waitcnt lgkmcnt(0)
	v_mfma_f32_16x16x32_bf16 v[64:67], v[154:157], v[186:189], v[64:67]
	v_mfma_f32_16x16x32_bf16 v[52:55], v[162:165], v[186:189], v[52:55]
	v_mfma_f32_16x16x32_bf16 v[44:47], v[154:157], v[194:197], v[44:47]
	v_mfma_f32_16x16x32_bf16 v[36:39], v[162:165], v[194:197], v[36:39]
	v_mfma_f32_16x16x32_bf16 v[28:31], v[154:157], v[202:205], v[28:31]
	v_mfma_f32_16x16x32_bf16 v[20:23], v[162:165], v[202:205], v[20:23]
	v_mfma_f32_16x16x32_bf16 v[12:15], v[154:157], v[210:213], v[12:15]
	v_mfma_f32_16x16x32_bf16 v[2:5], v[162:165], v[210:213], v[2:5]
	v_mfma_f32_16x16x32_bf16 v[64:67], v[158:161], v[190:193], v[64:67]
	v_mfma_f32_16x16x32_bf16 v[52:55], v[166:169], v[190:193], v[52:55]
	v_mfma_f32_16x16x32_bf16 v[44:47], v[158:161], v[198:201], v[44:47]
	v_mfma_f32_16x16x32_bf16 v[36:39], v[166:169], v[198:201], v[36:39]
	v_mfma_f32_16x16x32_bf16 v[28:31], v[158:161], v[206:209], v[28:31]
	v_mfma_f32_16x16x32_bf16 v[20:23], v[166:169], v[206:209], v[20:23]
	v_mfma_f32_16x16x32_bf16 v[12:15], v[158:161], v[214:217], v[12:15]
	v_mfma_f32_16x16x32_bf16 v[4:7], v[166:169], v[214:217], v[2:5]
	v_mfma_f32_16x16x32_bf16 v[72:75], v[170:173], v[186:189], v[72:75]
	v_mfma_f32_16x16x32_bf16 v[56:59], v[178:181], v[186:189], v[56:59]
	v_mfma_f32_16x16x32_bf16 v[48:51], v[170:173], v[194:197], v[48:51]
	v_mfma_f32_16x16x32_bf16 v[40:43], v[178:181], v[194:197], v[40:43]
	v_mfma_f32_16x16x32_bf16 v[32:35], v[170:173], v[202:205], v[32:35]
	v_mfma_f32_16x16x32_bf16 v[24:27], v[178:181], v[202:205], v[24:27]
	v_mfma_f32_16x16x32_bf16 v[16:19], v[170:173], v[210:213], v[16:19]
	v_mfma_f32_16x16x32_bf16 v[8:11], v[178:181], v[210:213], v[8:11]
	v_mfma_f32_16x16x32_bf16 v[72:75], v[174:177], v[190:193], v[72:75]
	v_mfma_f32_16x16x32_bf16 v[56:59], v[182:185], v[190:193], v[56:59]
	v_mfma_f32_16x16x32_bf16 v[48:51], v[174:177], v[198:201], v[48:51]
	v_mfma_f32_16x16x32_bf16 v[40:43], v[182:185], v[198:201], v[40:43]
	v_mfma_f32_16x16x32_bf16 v[32:35], v[174:177], v[206:209], v[32:35]
	v_mfma_f32_16x16x32_bf16 v[24:27], v[182:185], v[206:209], v[24:27]
	v_mfma_f32_16x16x32_bf16 v[16:19], v[174:177], v[214:217], v[16:19]
	v_mfma_f32_16x16x32_bf16 v[8:11], v[182:185], v[214:217], v[8:11]
	s_barrier
	s_add_i32 s70, s70, 2
	s_add_u32 s71, s71, 0x100
	s_addc_u32 s72, s72, 0
	s_cmp_gt_u32 s70, 13
	s_mov_b64 s[34:35], s[24:25]
	s_cbranch_scc0 .LBB0_2390
	s_and_b64 vcc, exec, s[12:13]
	s_cbranch_vccz .LBB0_2393
	v_mbcnt_lo_u32_b32 v188, -1, 0
	v_mbcnt_hi_u32_b32 v188, -1, v188
	v_lshlrev_b32_e32 v188, 2, v188
	v_add_u32_e32 v189, 0x23400, v188
	ds_read_b32 v189, v189
	s_waitcnt lgkmcnt(0)
	v_cmp_gt_u32_e32 vcc, 13, v189
	s_nop 3
	s_and_b32 vcc_lo, vcc_lo, 0xff
	s_cmp_eq_u32 vcc_lo, 0
	s_cbranch_scc1 .Lwok_2
	s_mov_b32 s100, 0
.Lwsl_2:
	v_add_u32_e32 v189, 0x4800, v188
	global_load_dword v189, v189, s[44:45] sc1
	s_waitcnt vmcnt(0)
	v_cmp_gt_u32_e32 vcc, 13, v189
	s_nop 3
	s_and_b32 vcc_lo, vcc_lo, 0xff
	s_cmp_eq_u32 vcc_lo, 0
	s_cbranch_scc1 .Lwok_2
	s_add_u32 s100, s100, 1
	s_cmp_lt_u32 s100, 0x4000
	s_cbranch_scc1 .Lwsl_2
